# NSA tile-scan loops: union-membership bit test done in SALU (cselect/lshr/and/cmp) instead of a VALU chain with VALU->SGPR compare
# speedup vs baseline: 1.0134x; 1.0089x over previous
;   DI bool farj(int j) const { return (j * 64 + 63 < q0) && (pqmin - posmax[j] >= 799); }
;   DI bool farj(int j) const { return (j * 64 + 63 < q0) && (pqmin - posmax[j] >= 799); }
;   DI int next(int t) const { for (int j = t + 1; j < 128; ++j) if (inu(j) && farj(j)) return j; return -1; }
;   DI bool inu(int j) const {
;     unsigned long long a = (ulo >> (j & 63)) & (j < 64 ? 1ull : 0ull);
;     unsigned long long b = (uhi >> (j & 63)) & (j >= 64 ? 1ull : 0ull);
;     return (a | b) != 0ull;
;   }
;   DI bool mine(int j) const {
;     unsigned long long a = (mlo >> (j & 63)) & (j < 64 ? 1ull : 0ull);
;     unsigned long long b = (mhi >> (j & 63)) & (j >= 64 ? 1ull : 0ull);
;     return (a | b) != 0ull;
;   }
;   DI int next(int t) const { for (int j = t + 1; j < 128; ++j) if (inu(j) && !farj(j)) return j; return -1; }
.LBB0_674:
	s_add_i32 s64, s54, 1
	s_cmp_lt_i32 s54, 63
	s_cselect_b64 s[12:13], s[14:15], s[52:53]
	s_lshr_b64 s[12:13], s[12:13], s64
	s_and_b32 s12, s12, 1
	s_cmp_eq_u32 s12, 0
	s_cselect_b64 vcc, -1, 0
	s_mov_b64 s[12:13], -1
	s_mov_b64 s[36:37], -1
	s_cbranch_vccnz .LBB0_677
	s_cmp_lt_i32 s47, s34
	s_mov_b64 s[36:37], 0
	s_cbranch_scc0 .LBB0_677
	s_lshl_b64 s[36:37], s[64:65], 2
	s_add_u32 s36, s44, s36
	s_addc_u32 s37, s45, s37
	s_load_dword s36, s[36:37], 0x0
	s_waitcnt vmcnt(0) lgkmcnt(0)
	v_subrev_u32_e32 v0, s36, v151
	v_cmp_lt_i32_e64 s[36:37], s93, v0

;   DI bool farj(int j) const { return (j * 64 + 63 < q0) && (pqmin - posmax[j] >= 799); }
;   DI int next(int t) const { for (int j = t + 1; j < 128; ++j) if (inu(j) && !farj(j)) return j; return -1; }
;   DI bool farj(int j) const { return (j * 64 + 63 < q0) && (pqmin - posmax[j] >= 799); }
;   DI bool inu(int j) const {
;     unsigned long long a = (ulo >> (j & 63)) & (j < 64 ? 1ull : 0ull);
;     unsigned long long b = (uhi >> (j & 63)) & (j >= 64 ? 1ull : 0ull);
;     return (a | b) != 0ull;
;   }
;   DI bool mine(int j) const {
;     unsigned long long a = (mlo >> (j & 63)) & (j < 64 ? 1ull : 0ull);
;     unsigned long long b = (mhi >> (j & 63)) & (j >= 64 ? 1ull : 0ull);
;     return (a | b) != 0ull;
;   }
;   DI int next(int t) const { for (int j = t + 1; j < 128; ++j) if (inu(j) && farj(j)) return j; return -1; }
.LBB0_767:
	s_add_i32 s64, s36, 1
	s_cmp_lt_i32 s36, 63
	s_cselect_b64 s[6:7], s[14:15], s[52:53]
	s_lshr_b64 s[6:7], s[6:7], s64
	s_and_b32 s6, s6, 1
	s_cmp_eq_u32 s6, 0
	s_cselect_b64 s[6:7], -1, 0
	s_and_b64 vcc, exec, s[6:7]
	s_cbranch_vccnz .LBB0_770
	s_cmp_ge_i32 s27, s34
	s_cselect_b64 s[6:7], -1, 0
	s_cmp_lt_i32 s27, s34
	s_cbranch_scc0 .LBB0_770
	s_lshl_b64 s[6:7], s[64:65], 2
	s_add_u32 s6, s44, s6
	s_addc_u32 s7, s45, s7
	s_load_dword s6, s[6:7], 0x0
	s_waitcnt vmcnt(0) lgkmcnt(0)
	v_subrev_u32_e32 v0, s6, v151
	v_cmp_gt_i32_e64 s[6:7], s89, v0
